# S5 mode-1 acquire of the chunk-prefix results via agent-scope (sc1) loads of the two carry-in words instead of a per-wave L2 invalidate
# speedup vs baseline: 1.0096x; 1.0026x over previous
.Lpfxw_done:
	s_nop 0
	s_nop 0
	s_branch .LBB0_640

.LBB0_642:
	v_lshl_or_b32 v112, s4, 5, v204
	v_lshlrev_b64 v[32:33], 10, v[112:113]
	v_lshlrev_b64 v[34:35], 12, v[112:113]
	v_lshl_add_u64 v[32:33], v[108:109], 0, v[32:33]
	v_lshl_add_u64 v[34:35], v[110:111], 0, v[34:35]
	v_lshlrev_b64 v[38:39], 13, v[112:113]
	global_load_dwordx2 v[118:119], v[32:33], off
	global_load_dwordx4 v[56:59], v[34:35], off
	global_load_dwordx4 v[60:63], v[34:35], off offset:1024
	global_load_dwordx4 v[64:67], v[34:35], off offset:2048
	v_lshl_add_u64 v[38:39], v[114:115], 0, v[38:39]
	global_load_dwordx4 v[68:71], v[34:35], off offset:3072
	global_load_dwordx4 v[72:75], v[38:39], off
	global_load_dwordx4 v[76:79], v[38:39], off offset:32
	global_load_dwordx4 v[80:83], v[38:39], off offset:64
	global_load_dwordx4 v[84:87], v[38:39], off offset:96
	global_load_dwordx4 v[88:91], v[38:39], off offset:128
	global_load_dwordx4 v[92:95], v[38:39], off offset:160
	global_load_dwordx4 v[96:99], v[38:39], off offset:192
	v_cndmask_b32_e64 v36, v201, v202, s[8:9]
	v_cndmask_b32_e64 v32, v201, v203, s[8:9]
	v_cndmask_b32_e64 v32, v36, v32, s[2:3]
	v_lshl_add_u32 v37, s4, 6, v197
	s_mov_b32 s4, 0x10800
	v_ashrrev_i32_e32 v33, 31, v32
	v_mad_i64_i32 v[36:37], s[4:5], v37, s4, v[116:117]
	v_lshlrev_b64 v[32:33], 9, v[32:33]
	v_lshl_add_u64 v[32:33], v[36:37], 0, v[32:33]
	global_load_dwordx4 v[100:103], v[38:39], off offset:224
	global_load_dword v112, v[32:33], off sc1
	global_load_dword v122, v[32:33], off offset:256 sc1
	s_and_b64 s[4:5], s[8:9], exec
	s_cselect_b32 s21, 0, 16
	s_lshl_b32 s20, s21, 1
	s_and_b64 s[4:5], s[8:9], exec
	s_cselect_b32 s23, 16, 0
	s_mulk_i32 s21, 0x110
	s_lshl_b32 s22, s23, 1
	s_mulk_i32 s23, 0x110
	s_xor_b64 s[10:11], s[8:9], -1
	s_mov_b64 s[12:13], -1
	s_waitcnt vmcnt(0) lgkmcnt(0)
	v_pk_mov_b32 v[120:121], v[118:119], v[118:119] op_sel:[1,0]
	s_branch .LBB0_644
